# convert_w for ffn w1/w3 and w2: all of a wave's 8x8 load groups issued up front (5-6 / 2-3 tasks in flight) instead of one group per loop trip
# speedup vs baseline: 1.0048x; 1.0048x over previous
; DI int TID() { int t = threadIdx.x; asm volatile("" : "+v"(t)); return t; }
; DI int BID() { int t = blockIdx.x; asm volatile("" : "+s"(t)); return t; }
; DI unsigned pk2(float a, float b) { f32x2_t v = {a, b}; bf16x2_t r = __builtin_convertvector(v, bf16x2_t); return __builtin_bit_cast(unsigned, r); }
; DI void convert_w(const float* src, const float* src2, int srcN, int K, bf16_t* dst, int Nd, int mode) {
;   const size_t gsz = (size_t)gridDim.x * NTHR, gid = (size_t)BID() * NTHR + TID();
;   const size_t total = (size_t)Nd * (K >> 3);
;   for (size_t e = gid; e < total; e += gsz) {
;     int nd = (int)(e % Nd), k0 = (int)(e / Nd) * 8;
;     const float* s = src; int col = nd; bool valid = true;
;     if (mode == 0) { valid = nd < srcN; }
;     else if (mode == 1) { int g = nd >> 6, w = nd & 63; if (w < 32) col = g * 32 + w; else { s = src2; col = g * 32 + w - 32; } }
;     else { if (nd < 1024) col = (nd >> 7) * 192 + (nd & 127); else { int r = nd - 1024; col = (r >> 6) * 192 + 128 + (r & 63); } }
;     float v[8];
; #pragma unroll
;     for (int j = 0; j < 8; ++j) v[j] = valid ? s[(size_t)(k0 + j) * srcN + col] : 0.f;
;     uint4 o; o.x = pk2(v[0], v[1]); o.y = pk2(v[2], v[3]); o.z = pk2(v[4], v[5]); o.w = pk2(v[6], v[7]);
;     *(uint4*)(dst + (size_t)nd * K + k0) = o;
;   }
.LBB0_945:
	s_lshr_b32 s30, s34, 6
	s_cmpk_lg_u32 s30, 0x800
	s_cbranch_scc1 .Lcv1_old
	v_lshrrev_b32_e32 v2, 6, v167
	v_and_b32_e32 v3, 63, v167
	s_lshl_b32 s25, s50, 3
	v_and_b32_e32 v4, 31, v3
	v_readfirstlane_b32 s24, v2
	v_cmp_gt_u32_e32 vcc, 32, v3
	v_mov_b32_e32 v5, s57
	v_mov_b32_e32 v6, s59
	v_mov_b32_e32 v7, s56
	v_mov_b32_e32 v8, s58
	s_add_u32 s25, s24, s25
	v_cndmask_b32_e32 v11, v6, v5, vcc
	v_cndmask_b32_e32 v10, v8, v7, vcc
	v_lshl_add_u64 v[10:11], v[10:11], 0, s[0:1]
	v_lshlrev_b32_e32 v140, 2, v4
	v_lshl_add_u64 v[10:11], v[10:11], 0, v[140:141]
	s_mov_b64 s[36:37], 0x2c00
	v_lshl_add_u64 v[12:13], v[10:11], 0, s[36:37]
	s_mov_b64 s[36:37], 0x5800
	v_lshl_add_u64 v[14:15], v[10:11], 0, s[36:37]
	s_mov_b64 s[36:37], 0x8400
	v_lshl_add_u64 v[16:17], v[10:11], 0, s[36:37]
	s_mov_b64 s[36:37], 0xb000
	v_lshl_add_u64 v[18:19], v[10:11], 0, s[36:37]
	s_mov_b64 s[36:37], 0xdc00
	v_lshl_add_u64 v[20:21], v[10:11], 0, s[36:37]
	s_mov_b64 s[36:37], 0x10800
	v_lshl_add_u64 v[22:23], v[10:11], 0, s[36:37]
	s_mov_b64 s[36:37], 0x13400
	v_lshl_add_u64 v[24:25], v[10:11], 0, s[36:37]
	v_lshlrev_b32_e32 v140, 11, v3
	v_lshl_add_u64 v[28:29], s[20:21], 0, v[140:141]
	s_mov_b32 s39, 0
	s_cmpk_lt_u32 s25, 0x400
	s_cbranch_scc0 .Lcv1_n5
	s_mov_b32 s31, s25
	s_mul_hi_u32 s36, s31, 0x2e8ba2f
	s_mul_i32 s37, s36, 0x58
	s_sub_u32 s37, s31, s37
	s_mul_i32 s38, s36, 0x16000
	s_lshl_b32 s3, s37, 7
	s_add_u32 s38, s38, s3
	s_lshl_b32 s3, s37, 17
	s_lshl_b32 s24, s36, 4
	s_add_u32 s3, s3, s24
	v_mov_b32_e32 v90, s3
	v_lshl_add_u64 v[30:31], v[10:11], 0, s[38:39]
	global_load_dword v40, v[30:31], off
	v_lshl_add_u64 v[32:33], v[12:13], 0, s[38:39]
	global_load_dword v41, v[32:33], off
	v_lshl_add_u64 v[30:31], v[14:15], 0, s[38:39]
	global_load_dword v42, v[30:31], off
	v_lshl_add_u64 v[32:33], v[16:17], 0, s[38:39]
	global_load_dword v43, v[32:33], off
	v_lshl_add_u64 v[30:31], v[18:19], 0, s[38:39]
	global_load_dword v44, v[30:31], off
	v_lshl_add_u64 v[32:33], v[20:21], 0, s[38:39]
	global_load_dword v45, v[32:33], off
	v_lshl_add_u64 v[30:31], v[22:23], 0, s[38:39]
	global_load_dword v46, v[30:31], off
	v_lshl_add_u64 v[32:33], v[24:25], 0, s[38:39]
	global_load_dword v47, v[32:33], off
	s_add_u32 s31, s31, s30
	s_mul_hi_u32 s36, s31, 0x2e8ba2f
	s_mul_i32 s37, s36, 0x58
	s_sub_u32 s37, s31, s37
	s_mul_i32 s38, s36, 0x16000
	s_lshl_b32 s3, s37, 7
	s_add_u32 s38, s38, s3
	s_lshl_b32 s3, s37, 17
	s_lshl_b32 s24, s36, 4
	s_add_u32 s3, s3, s24
	v_mov_b32_e32 v91, s3
	v_lshl_add_u64 v[30:31], v[10:11], 0, s[38:39]
	global_load_dword v48, v[30:31], off
	v_lshl_add_u64 v[32:33], v[12:13], 0, s[38:39]
	global_load_dword v49, v[32:33], off
	v_lshl_add_u64 v[30:31], v[14:15], 0, s[38:39]
	global_load_dword v50, v[30:31], off
	v_lshl_add_u64 v[32:33], v[16:17], 0, s[38:39]
	global_load_dword v51, v[32:33], off
	v_lshl_add_u64 v[30:31], v[18:19], 0, s[38:39]
	global_load_dword v52, v[30:31], off
	v_lshl_add_u64 v[32:33], v[20:21], 0, s[38:39]
	global_load_dword v53, v[32:33], off
	v_lshl_add_u64 v[30:31], v[22:23], 0, s[38:39]
	global_load_dword v54, v[30:31], off
	v_lshl_add_u64 v[32:33], v[24:25], 0, s[38:39]
	global_load_dword v55, v[32:33], off
	s_add_u32 s31, s31, s30
	s_mul_hi_u32 s36, s31, 0x2e8ba2f
	s_mul_i32 s37, s36, 0x58
	s_sub_u32 s37, s31, s37
	s_mul_i32 s38, s36, 0x16000
	s_lshl_b32 s3, s37, 7
	s_add_u32 s38, s38, s3
	s_lshl_b32 s3, s37, 17
	s_lshl_b32 s24, s36, 4
	s_add_u32 s3, s3, s24
	v_mov_b32_e32 v92, s3
	v_lshl_add_u64 v[30:31], v[10:11], 0, s[38:39]
	global_load_dword v56, v[30:31], off
	v_lshl_add_u64 v[32:33], v[12:13], 0, s[38:39]
	global_load_dword v57, v[32:33], off
	v_lshl_add_u64 v[30:31], v[14:15], 0, s[38:39]
	global_load_dword v58, v[30:31], off
	v_lshl_add_u64 v[32:33], v[16:17], 0, s[38:39]
	global_load_dword v59, v[32:33], off
	v_lshl_add_u64 v[30:31], v[18:19], 0, s[38:39]
	global_load_dword v60, v[30:31], off
	v_lshl_add_u64 v[32:33], v[20:21], 0, s[38:39]
	global_load_dword v61, v[32:33], off
	v_lshl_add_u64 v[30:31], v[22:23], 0, s[38:39]
	global_load_dword v62, v[30:31], off
	v_lshl_add_u64 v[32:33], v[24:25], 0, s[38:39]
	global_load_dword v63, v[32:33], off
	s_add_u32 s31, s31, s30
	s_mul_hi_u32 s36, s31, 0x2e8ba2f
	s_mul_i32 s37, s36, 0x58
	s_sub_u32 s37, s31, s37
	s_mul_i32 s38, s36, 0x16000
	s_lshl_b32 s3, s37, 7
	s_add_u32 s38, s38, s3
	s_lshl_b32 s3, s37, 17
	s_lshl_b32 s24, s36, 4
	s_add_u32 s3, s3, s24
	v_mov_b32_e32 v93, s3
	v_lshl_add_u64 v[30:31], v[10:11], 0, s[38:39]
	global_load_dword v64, v[30:31], off
	v_lshl_add_u64 v[32:33], v[12:13], 0, s[38:39]
	global_load_dword v65, v[32:33], off
	v_lshl_add_u64 v[30:31], v[14:15], 0, s[38:39]
	global_load_dword v66, v[30:31], off
	v_lshl_add_u64 v[32:33], v[16:17], 0, s[38:39]
	global_load_dword v67, v[32:33], off
	v_lshl_add_u64 v[30:31], v[18:19], 0, s[38:39]
	global_load_dword v68, v[30:31], off
	v_lshl_add_u64 v[32:33], v[20:21], 0, s[38:39]
	global_load_dword v69, v[32:33], off
	v_lshl_add_u64 v[30:31], v[22:23], 0, s[38:39]
	global_load_dword v70, v[30:31], off
	v_lshl_add_u64 v[32:33], v[24:25], 0, s[38:39]
	global_load_dword v71, v[32:33], off
	s_add_u32 s31, s31, s30
	s_mul_hi_u32 s36, s31, 0x2e8ba2f
	s_mul_i32 s37, s36, 0x58
	s_sub_u32 s37, s31, s37
	s_mul_i32 s38, s36, 0x16000
	s_lshl_b32 s3, s37, 7
	s_add_u32 s38, s38, s3
	s_lshl_b32 s3, s37, 17
	s_lshl_b32 s24, s36, 4
	s_add_u32 s3, s3, s24
	v_mov_b32_e32 v94, s3
	v_lshl_add_u64 v[30:31], v[10:11], 0, s[38:39]
	global_load_dword v72, v[30:31], off
	v_lshl_add_u64 v[32:33], v[12:13], 0, s[38:39]
	global_load_dword v73, v[32:33], off
	v_lshl_add_u64 v[30:31], v[14:15], 0, s[38:39]
; DI unsigned pk2(float a, float b) { f32x2_t v = {a, b}; bf16x2_t r = __builtin_convertvector(v, bf16x2_t); return __builtin_bit_cast(unsigned, r); }
; DI void convert_w(const float* src, const float* src2, int srcN, int K, bf16_t* dst, int Nd, int mode) {
;     ...
;   for (size_t e = gid; e < total; e += gsz) {
;     int nd = (int)(e % Nd), k0 = (int)(e / Nd) * 8;
;     const float* s = src; int col = nd; bool valid = true;
;     if (mode == 0) { valid = nd < srcN; }
;     else if (mode == 1) { int g = nd >> 6, w = nd & 63; if (w < 32) col = g * 32 + w; else { s = src2; col = g * 32 + w - 32; } }
;     else { if (nd < 1024) col = (nd >> 7) * 192 + (nd & 127); else { int r = nd - 1024; col = (r >> 6) * 192 + 128 + (r & 63); } }
;     float v[8];
; #pragma unroll
;     for (int j = 0; j < 8; ++j) v[j] = valid ? s[(size_t)(k0 + j) * srcN + col] : 0.f;
;     uint4 o; o.x = pk2(v[0], v[1]); o.y = pk2(v[2], v[3]); o.z = pk2(v[4], v[5]); o.w = pk2(v[6], v[7]);
;     *(uint4*)(dst + (size_t)nd * K + k0) = o;
;   }
	global_load_dword v74, v[30:31], off
	v_lshl_add_u64 v[32:33], v[16:17], 0, s[38:39]
	global_load_dword v75, v[32:33], off
	v_lshl_add_u64 v[30:31], v[18:19], 0, s[38:39]
	global_load_dword v76, v[30:31], off
	v_lshl_add_u64 v[32:33], v[20:21], 0, s[38:39]
	global_load_dword v77, v[32:33], off
	v_lshl_add_u64 v[30:31], v[22:23], 0, s[38:39]
	global_load_dword v78, v[30:31], off
	v_lshl_add_u64 v[32:33], v[24:25], 0, s[38:39]
	global_load_dword v79, v[32:33], off
	s_add_u32 s31, s31, s30
	s_mul_hi_u32 s36, s31, 0x2e8ba2f
	s_mul_i32 s37, s36, 0x58
	s_sub_u32 s37, s31, s37
	s_mul_i32 s38, s36, 0x16000
	s_lshl_b32 s3, s37, 7
	s_add_u32 s38, s38, s3
	s_lshl_b32 s3, s37, 17
	s_lshl_b32 s24, s36, 4
	s_add_u32 s3, s3, s24
	v_mov_b32_e32 v95, s3
	v_lshl_add_u64 v[30:31], v[10:11], 0, s[38:39]
	global_load_dword v80, v[30:31], off
	v_lshl_add_u64 v[32:33], v[12:13], 0, s[38:39]
	global_load_dword v81, v[32:33], off
	v_lshl_add_u64 v[30:31], v[14:15], 0, s[38:39]
	global_load_dword v82, v[30:31], off
	v_lshl_add_u64 v[32:33], v[16:17], 0, s[38:39]
	global_load_dword v83, v[32:33], off
	v_lshl_add_u64 v[30:31], v[18:19], 0, s[38:39]
	global_load_dword v84, v[30:31], off
	v_lshl_add_u64 v[32:33], v[20:21], 0, s[38:39]
	global_load_dword v85, v[32:33], off
	v_lshl_add_u64 v[30:31], v[22:23], 0, s[38:39]
	global_load_dword v86, v[30:31], off
	v_lshl_add_u64 v[32:33], v[24:25], 0, s[38:39]
	global_load_dword v87, v[32:33], off
	s_waitcnt vmcnt(40)
	v_cvt_pk_bf16_f32 v100, v40, v41
	v_cvt_pk_bf16_f32 v101, v42, v43
	v_cvt_pk_bf16_f32 v102, v44, v45
	v_cvt_pk_bf16_f32 v103, v46, v47
	v_mov_b32_e32 v140, v90
	v_lshl_add_u64 v[34:35], v[28:29], 0, v[140:141]
	global_store_dwordx4 v[34:35], v[100:103], off
	s_waitcnt vmcnt(33)
	v_cvt_pk_bf16_f32 v104, v48, v49
	v_cvt_pk_bf16_f32 v105, v50, v51
	v_cvt_pk_bf16_f32 v106, v52, v53
	v_cvt_pk_bf16_f32 v107, v54, v55
	v_mov_b32_e32 v140, v91
	v_lshl_add_u64 v[34:35], v[28:29], 0, v[140:141]
	global_store_dwordx4 v[34:35], v[104:107], off
	s_waitcnt vmcnt(26)
	v_cvt_pk_bf16_f32 v108, v56, v57
	v_cvt_pk_bf16_f32 v109, v58, v59
	v_cvt_pk_bf16_f32 v110, v60, v61
	v_cvt_pk_bf16_f32 v111, v62, v63
	v_mov_b32_e32 v140, v92
	v_lshl_add_u64 v[34:35], v[28:29], 0, v[140:141]
	global_store_dwordx4 v[34:35], v[108:111], off
	s_waitcnt vmcnt(19)
	v_cvt_pk_bf16_f32 v112, v64, v65
	v_cvt_pk_bf16_f32 v113, v66, v67
	v_cvt_pk_bf16_f32 v114, v68, v69
	v_cvt_pk_bf16_f32 v115, v70, v71
	v_mov_b32_e32 v140, v93
	v_lshl_add_u64 v[34:35], v[28:29], 0, v[140:141]
	global_store_dwordx4 v[34:35], v[112:115], off
	s_waitcnt vmcnt(12)
	v_cvt_pk_bf16_f32 v116, v72, v73
	v_cvt_pk_bf16_f32 v117, v74, v75
	v_cvt_pk_bf16_f32 v118, v76, v77
	v_cvt_pk_bf16_f32 v119, v78, v79
	v_mov_b32_e32 v140, v94
	v_lshl_add_u64 v[34:35], v[28:29], 0, v[140:141]
	global_store_dwordx4 v[34:35], v[116:119], off
	s_waitcnt vmcnt(5)
	v_cvt_pk_bf16_f32 v120, v80, v81
	v_cvt_pk_bf16_f32 v121, v82, v83
	v_cvt_pk_bf16_f32 v122, v84, v85
	v_cvt_pk_bf16_f32 v123, v86, v87
	v_mov_b32_e32 v140, v95
	v_lshl_add_u64 v[34:35], v[28:29], 0, v[140:141]
	global_store_dwordx4 v[34:35], v[120:123], off
	s_branch .LBB0_946
; DI unsigned pk2(float a, float b) { f32x2_t v = {a, b}; bf16x2_t r = __builtin_convertvector(v, bf16x2_t); return __builtin_bit_cast(unsigned, r); }
; DI void convert_w(const float* src, const float* src2, int srcN, int K, bf16_t* dst, int Nd, int mode) {
;     ...
;   for (size_t e = gid; e < total; e += gsz) {
;     int nd = (int)(e % Nd), k0 = (int)(e / Nd) * 8;
;     const float* s = src; int col = nd; bool valid = true;
;     if (mode == 0) { valid = nd < srcN; }
;     else if (mode == 1) { int g = nd >> 6, w = nd & 63; if (w < 32) col = g * 32 + w; else { s = src2; col = g * 32 + w - 32; } }
;     else { if (nd < 1024) col = (nd >> 7) * 192 + (nd & 127); else { int r = nd - 1024; col = (r >> 6) * 192 + 128 + (r & 63); } }
;     float v[8];
; #pragma unroll
;     for (int j = 0; j < 8; ++j) v[j] = valid ? s[(size_t)(k0 + j) * srcN + col] : 0.f;
;     uint4 o; o.x = pk2(v[0], v[1]); o.y = pk2(v[2], v[3]); o.z = pk2(v[4], v[5]); o.w = pk2(v[6], v[7]);
;     *(uint4*)(dst + (size_t)nd * K + k0) = o;
;   }
.Lcv1_n5:
	s_mov_b32 s31, s25
	s_mul_hi_u32 s36, s31, 0x2e8ba2f
	s_mul_i32 s37, s36, 0x58
	s_sub_u32 s37, s31, s37
	s_mul_i32 s38, s36, 0x16000
	s_lshl_b32 s3, s37, 7
	s_add_u32 s38, s38, s3
	s_lshl_b32 s3, s37, 17
	s_lshl_b32 s24, s36, 4
	s_add_u32 s3, s3, s24
	v_mov_b32_e32 v90, s3
	v_lshl_add_u64 v[30:31], v[10:11], 0, s[38:39]
	global_load_dword v40, v[30:31], off
	v_lshl_add_u64 v[32:33], v[12:13], 0, s[38:39]
	global_load_dword v41, v[32:33], off
	v_lshl_add_u64 v[30:31], v[14:15], 0, s[38:39]
	global_load_dword v42, v[30:31], off
	v_lshl_add_u64 v[32:33], v[16:17], 0, s[38:39]
	global_load_dword v43, v[32:33], off
	v_lshl_add_u64 v[30:31], v[18:19], 0, s[38:39]
	global_load_dword v44, v[30:31], off
	v_lshl_add_u64 v[32:33], v[20:21], 0, s[38:39]
	global_load_dword v45, v[32:33], off
	v_lshl_add_u64 v[30:31], v[22:23], 0, s[38:39]
	global_load_dword v46, v[30:31], off
	v_lshl_add_u64 v[32:33], v[24:25], 0, s[38:39]
	global_load_dword v47, v[32:33], off
	s_add_u32 s31, s31, s30
	s_mul_hi_u32 s36, s31, 0x2e8ba2f
	s_mul_i32 s37, s36, 0x58
	s_sub_u32 s37, s31, s37
	s_mul_i32 s38, s36, 0x16000
	s_lshl_b32 s3, s37, 7
	s_add_u32 s38, s38, s3
	s_lshl_b32 s3, s37, 17
	s_lshl_b32 s24, s36, 4
	s_add_u32 s3, s3, s24
	v_mov_b32_e32 v91, s3
	v_lshl_add_u64 v[30:31], v[10:11], 0, s[38:39]
	global_load_dword v48, v[30:31], off
	v_lshl_add_u64 v[32:33], v[12:13], 0, s[38:39]
	global_load_dword v49, v[32:33], off
	v_lshl_add_u64 v[30:31], v[14:15], 0, s[38:39]
	global_load_dword v50, v[30:31], off
	v_lshl_add_u64 v[32:33], v[16:17], 0, s[38:39]
	global_load_dword v51, v[32:33], off
	v_lshl_add_u64 v[30:31], v[18:19], 0, s[38:39]
	global_load_dword v52, v[30:31], off
	v_lshl_add_u64 v[32:33], v[20:21], 0, s[38:39]
	global_load_dword v53, v[32:33], off
	v_lshl_add_u64 v[30:31], v[22:23], 0, s[38:39]
	global_load_dword v54, v[30:31], off
	v_lshl_add_u64 v[32:33], v[24:25], 0, s[38:39]
	global_load_dword v55, v[32:33], off
	s_add_u32 s31, s31, s30
	s_mul_hi_u32 s36, s31, 0x2e8ba2f
	s_mul_i32 s37, s36, 0x58
	s_sub_u32 s37, s31, s37
	s_mul_i32 s38, s36, 0x16000
	s_lshl_b32 s3, s37, 7
	s_add_u32 s38, s38, s3
	s_lshl_b32 s3, s37, 17
	s_lshl_b32 s24, s36, 4
	s_add_u32 s3, s3, s24
	v_mov_b32_e32 v92, s3
	v_lshl_add_u64 v[30:31], v[10:11], 0, s[38:39]
	global_load_dword v56, v[30:31], off
	v_lshl_add_u64 v[32:33], v[12:13], 0, s[38:39]
	global_load_dword v57, v[32:33], off
	v_lshl_add_u64 v[30:31], v[14:15], 0, s[38:39]
	global_load_dword v58, v[30:31], off
	v_lshl_add_u64 v[32:33], v[16:17], 0, s[38:39]
	global_load_dword v59, v[32:33], off
	v_lshl_add_u64 v[30:31], v[18:19], 0, s[38:39]
	global_load_dword v60, v[30:31], off
	v_lshl_add_u64 v[32:33], v[20:21], 0, s[38:39]
	global_load_dword v61, v[32:33], off
	v_lshl_add_u64 v[30:31], v[22:23], 0, s[38:39]
	global_load_dword v62, v[30:31], off
	v_lshl_add_u64 v[32:33], v[24:25], 0, s[38:39]
	global_load_dword v63, v[32:33], off
	s_add_u32 s31, s31, s30
	s_mul_hi_u32 s36, s31, 0x2e8ba2f
	s_mul_i32 s37, s36, 0x58
	s_sub_u32 s37, s31, s37
	s_mul_i32 s38, s36, 0x16000
	s_lshl_b32 s3, s37, 7
	s_add_u32 s38, s38, s3
	s_lshl_b32 s3, s37, 17
	s_lshl_b32 s24, s36, 4
	s_add_u32 s3, s3, s24
	v_mov_b32_e32 v93, s3
	v_lshl_add_u64 v[30:31], v[10:11], 0, s[38:39]
	global_load_dword v64, v[30:31], off
	v_lshl_add_u64 v[32:33], v[12:13], 0, s[38:39]
	global_load_dword v65, v[32:33], off
	v_lshl_add_u64 v[30:31], v[14:15], 0, s[38:39]
	global_load_dword v66, v[30:31], off
	v_lshl_add_u64 v[32:33], v[16:17], 0, s[38:39]
	global_load_dword v67, v[32:33], off
	v_lshl_add_u64 v[30:31], v[18:19], 0, s[38:39]
	global_load_dword v68, v[30:31], off
	v_lshl_add_u64 v[32:33], v[20:21], 0, s[38:39]
	global_load_dword v69, v[32:33], off
	v_lshl_add_u64 v[30:31], v[22:23], 0, s[38:39]
	global_load_dword v70, v[30:31], off
	v_lshl_add_u64 v[32:33], v[24:25], 0, s[38:39]
	global_load_dword v71, v[32:33], off
	s_add_u32 s31, s31, s30
	s_mul_hi_u32 s36, s31, 0x2e8ba2f
	s_mul_i32 s37, s36, 0x58
	s_sub_u32 s37, s31, s37
	s_mul_i32 s38, s36, 0x16000
	s_lshl_b32 s3, s37, 7
	s_add_u32 s38, s38, s3
	s_lshl_b32 s3, s37, 17
	s_lshl_b32 s24, s36, 4
	s_add_u32 s3, s3, s24
	v_mov_b32_e32 v94, s3
	v_lshl_add_u64 v[30:31], v[10:11], 0, s[38:39]
	global_load_dword v72, v[30:31], off
	v_lshl_add_u64 v[32:33], v[12:13], 0, s[38:39]
	global_load_dword v73, v[32:33], off
	v_lshl_add_u64 v[30:31], v[14:15], 0, s[38:39]
	global_load_dword v74, v[30:31], off
	v_lshl_add_u64 v[32:33], v[16:17], 0, s[38:39]
	global_load_dword v75, v[32:33], off
	v_lshl_add_u64 v[30:31], v[18:19], 0, s[38:39]
	global_load_dword v76, v[30:31], off
	v_lshl_add_u64 v[32:33], v[20:21], 0, s[38:39]
	global_load_dword v77, v[32:33], off
	v_lshl_add_u64 v[30:31], v[22:23], 0, s[38:39]
	global_load_dword v78, v[30:31], off
	v_lshl_add_u64 v[32:33], v[24:25], 0, s[38:39]
	global_load_dword v79, v[32:33], off
	s_waitcnt vmcnt(32)
	v_cvt_pk_bf16_f32 v100, v40, v41
	v_cvt_pk_bf16_f32 v101, v42, v43
	v_cvt_pk_bf16_f32 v102, v44, v45
	v_cvt_pk_bf16_f32 v103, v46, v47
	v_mov_b32_e32 v140, v90
	v_lshl_add_u64 v[34:35], v[28:29], 0, v[140:141]
	global_store_dwordx4 v[34:35], v[100:103], off
	s_waitcnt vmcnt(25)
	v_cvt_pk_bf16_f32 v104, v48, v49
	v_cvt_pk_bf16_f32 v105, v50, v51
	v_cvt_pk_bf16_f32 v106, v52, v53
	v_cvt_pk_bf16_f32 v107, v54, v55
	v_mov_b32_e32 v140, v91
	v_lshl_add_u64 v[34:35], v[28:29], 0, v[140:141]
	global_store_dwordx4 v[34:35], v[104:107], off
	s_waitcnt vmcnt(18)
	v_cvt_pk_bf16_f32 v108, v56, v57
	v_cvt_pk_bf16_f32 v109, v58, v59
	v_cvt_pk_bf16_f32 v110, v60, v61
	v_cvt_pk_bf16_f32 v111, v62, v63
	v_mov_b32_e32 v140, v92
	v_lshl_add_u64 v[34:35], v[28:29], 0, v[140:141]
	global_store_dwordx4 v[34:35], v[108:111], off
	s_waitcnt vmcnt(11)
	v_cvt_pk_bf16_f32 v112, v64, v65
	v_cvt_pk_bf16_f32 v113, v66, v67
	v_cvt_pk_bf16_f32 v114, v68, v69
	v_cvt_pk_bf16_f32 v115, v70, v71
	v_mov_b32_e32 v140, v93
	v_lshl_add_u64 v[34:35], v[28:29], 0, v[140:141]
	global_store_dwordx4 v[34:35], v[112:115], off
	s_waitcnt vmcnt(4)
	v_cvt_pk_bf16_f32 v116, v72, v73
	v_cvt_pk_bf16_f32 v117, v74, v75
	v_cvt_pk_bf16_f32 v118, v76, v77
	v_cvt_pk_bf16_f32 v119, v78, v79
	v_mov_b32_e32 v140, v94
	v_lshl_add_u64 v[34:35], v[28:29], 0, v[140:141]
	global_store_dwordx4 v[34:35], v[116:119], off
	s_branch .LBB0_946
.Lcv1_old:
	s_mov_b64 s[30:31], 0

; DI int TID() { int t = threadIdx.x; asm volatile("" : "+v"(t)); return t; }
; DI int BID() { int t = blockIdx.x; asm volatile("" : "+s"(t)); return t; }
; DI unsigned pk2(float a, float b) { f32x2_t v = {a, b}; bf16x2_t r = __builtin_convertvector(v, bf16x2_t); return __builtin_bit_cast(unsigned, r); }
; DI void convert_w(const float* src, const float* src2, int srcN, int K, bf16_t* dst, int Nd, int mode) {
;   const size_t gsz = (size_t)gridDim.x * NTHR, gid = (size_t)BID() * NTHR + TID();
;   const size_t total = (size_t)Nd * (K >> 3);
;   for (size_t e = gid; e < total; e += gsz) {
;     int nd = (int)(e % Nd), k0 = (int)(e / Nd) * 8;
;     const float* s = src; int col = nd; bool valid = true;
;     if (mode == 0) { valid = nd < srcN; }
;     else if (mode == 1) { int g = nd >> 6, w = nd & 63; if (w < 32) col = g * 32 + w; else { s = src2; col = g * 32 + w - 32; } }
;     else { if (nd < 1024) col = (nd >> 7) * 192 + (nd & 127); else { int r = nd - 1024; col = (r >> 6) * 192 + 128 + (r & 63); } }
;     float v[8];
; #pragma unroll
;     for (int j = 0; j < 8; ++j) v[j] = valid ? s[(size_t)(k0 + j) * srcN + col] : 0.f;
;     uint4 o; o.x = pk2(v[0], v[1]); o.y = pk2(v[2], v[3]); o.z = pk2(v[4], v[5]); o.w = pk2(v[6], v[7]);
;     *(uint4*)(dst + (size_t)nd * K + k0) = o;
;   }
.LBB0_948:
	s_lshr_b32 s30, s36, 6
	s_cmpk_lg_u32 s30, 0x800
	s_cbranch_scc1 .Lcv2_old
	v_lshrrev_b32_e32 v2, 6, v167
	v_and_b32_e32 v3, 63, v167
	s_lshl_b32 s25, s50, 3
	v_lshlrev_b32_e32 v140, 2, v3
	v_readfirstlane_b32 s24, v2
	v_lshl_add_u64 v[10:11], s[0:1], 0, v[140:141]
	s_nop 1
	s_add_u32 s25, s24, s25
	s_mov_b64 s[38:39], 0x1000
	v_lshl_add_u64 v[12:13], v[10:11], 0, s[38:39]
	s_mov_b64 s[38:39], 0x2000
	v_lshl_add_u64 v[14:15], v[10:11], 0, s[38:39]
	s_mov_b64 s[38:39], 0x3000
	v_lshl_add_u64 v[16:17], v[10:11], 0, s[38:39]
	s_mov_b64 s[38:39], 0x4000
	v_lshl_add_u64 v[18:19], v[10:11], 0, s[38:39]
	s_mov_b64 s[38:39], 0x5000
	v_lshl_add_u64 v[20:21], v[10:11], 0, s[38:39]
	s_mov_b64 s[38:39], 0x6000
	v_lshl_add_u64 v[22:23], v[10:11], 0, s[38:39]
	s_mov_b64 s[38:39], 0x7000
	v_lshl_add_u64 v[24:25], v[10:11], 0, s[38:39]
	v_mul_u32_u24_e32 v140, 0x1600, v3
	v_lshl_add_u64 v[28:29], s[34:35], 0, v[140:141]
	s_mov_b32 s39, 0
	s_cmpk_lt_u32 s25, 0x600
	s_cbranch_scc0 .Lcv2_n2
	s_mov_b32 s31, s25
	s_lshr_b32 s24, s31, 4
	s_and_b32 s38, s31, 15
	s_mul_i32 s3, s38, 0x58000
	s_lshl_b32 s38, s38, 8
	s_lshl_b32 s37, s24, 4
	s_add_u32 s3, s3, s37
	s_lshl_b32 s37, s24, 15
	s_add_u32 s38, s38, s37
	s_mov_b32 s37, 0
	v_mov_b32_e32 v90, s3
	v_lshl_add_u64 v[30:31], v[10:11], 0, s[38:39]
	global_load_dword v40, v[30:31], off
	v_lshl_add_u64 v[32:33], v[12:13], 0, s[38:39]
	global_load_dword v41, v[32:33], off
	v_lshl_add_u64 v[30:31], v[14:15], 0, s[38:39]
	global_load_dword v42, v[30:31], off
	v_lshl_add_u64 v[32:33], v[16:17], 0, s[38:39]
	global_load_dword v43, v[32:33], off
	v_lshl_add_u64 v[30:31], v[18:19], 0, s[38:39]
	global_load_dword v44, v[30:31], off
	v_lshl_add_u64 v[32:33], v[20:21], 0, s[38:39]
	global_load_dword v45, v[32:33], off
	v_lshl_add_u64 v[30:31], v[22:23], 0, s[38:39]
	global_load_dword v46, v[30:31], off
	v_lshl_add_u64 v[32:33], v[24:25], 0, s[38:39]
	global_load_dword v47, v[32:33], off
	s_add_u32 s31, s31, s30
	s_lshr_b32 s24, s31, 4
	s_and_b32 s38, s31, 15
	s_mul_i32 s3, s38, 0x58000
	s_lshl_b32 s38, s38, 8
	s_lshl_b32 s37, s24, 4
	s_add_u32 s3, s3, s37
	s_lshl_b32 s37, s24, 15
	s_add_u32 s38, s38, s37
	s_mov_b32 s37, 0
	v_mov_b32_e32 v91, s3
	v_lshl_add_u64 v[30:31], v[10:11], 0, s[38:39]
	global_load_dword v48, v[30:31], off
	v_lshl_add_u64 v[32:33], v[12:13], 0, s[38:39]
	global_load_dword v49, v[32:33], off
	v_lshl_add_u64 v[30:31], v[14:15], 0, s[38:39]
	global_load_dword v50, v[30:31], off
	v_lshl_add_u64 v[32:33], v[16:17], 0, s[38:39]
	global_load_dword v51, v[32:33], off
	v_lshl_add_u64 v[30:31], v[18:19], 0, s[38:39]
	global_load_dword v52, v[30:31], off
	v_lshl_add_u64 v[32:33], v[20:21], 0, s[38:39]
	global_load_dword v53, v[32:33], off
	v_lshl_add_u64 v[30:31], v[22:23], 0, s[38:39]
	global_load_dword v54, v[30:31], off
	v_lshl_add_u64 v[32:33], v[24:25], 0, s[38:39]
	global_load_dword v55, v[32:33], off
	s_add_u32 s31, s31, s30
	s_lshr_b32 s24, s31, 4
	s_and_b32 s38, s31, 15
	s_mul_i32 s3, s38, 0x58000
	s_lshl_b32 s38, s38, 8
	s_lshl_b32 s37, s24, 4
	s_add_u32 s3, s3, s37
	s_lshl_b32 s37, s24, 15
	s_add_u32 s38, s38, s37
	s_mov_b32 s37, 0
	v_mov_b32_e32 v92, s3
	v_lshl_add_u64 v[30:31], v[10:11], 0, s[38:39]
	global_load_dword v56, v[30:31], off
	v_lshl_add_u64 v[32:33], v[12:13], 0, s[38:39]
	global_load_dword v57, v[32:33], off
	v_lshl_add_u64 v[30:31], v[14:15], 0, s[38:39]
	global_load_dword v58, v[30:31], off
	v_lshl_add_u64 v[32:33], v[16:17], 0, s[38:39]
	global_load_dword v59, v[32:33], off
	v_lshl_add_u64 v[30:31], v[18:19], 0, s[38:39]
	global_load_dword v60, v[30:31], off
	v_lshl_add_u64 v[32:33], v[20:21], 0, s[38:39]
	global_load_dword v61, v[32:33], off
	v_lshl_add_u64 v[30:31], v[22:23], 0, s[38:39]
	global_load_dword v62, v[30:31], off
	v_lshl_add_u64 v[32:33], v[24:25], 0, s[38:39]
	global_load_dword v63, v[32:33], off
	s_waitcnt vmcnt(16)
	v_cvt_pk_bf16_f32 v100, v40, v41
	v_cvt_pk_bf16_f32 v101, v42, v43
	v_cvt_pk_bf16_f32 v102, v44, v45
	v_cvt_pk_bf16_f32 v103, v46, v47
	v_mov_b32_e32 v140, v90
	v_lshl_add_u64 v[34:35], v[28:29], 0, v[140:141]
	global_store_dwordx4 v[34:35], v[100:103], off
	s_waitcnt vmcnt(9)
	v_cvt_pk_bf16_f32 v104, v48, v49
	v_cvt_pk_bf16_f32 v105, v50, v51
	v_cvt_pk_bf16_f32 v106, v52, v53
	v_cvt_pk_bf16_f32 v107, v54, v55
	v_mov_b32_e32 v140, v91
	v_lshl_add_u64 v[34:35], v[28:29], 0, v[140:141]
	global_store_dwordx4 v[34:35], v[104:107], off
	s_waitcnt vmcnt(2)
	v_cvt_pk_bf16_f32 v108, v56, v57
	v_cvt_pk_bf16_f32 v109, v58, v59
	v_cvt_pk_bf16_f32 v110, v60, v61
	v_cvt_pk_bf16_f32 v111, v62, v63
	v_mov_b32_e32 v140, v92
	v_lshl_add_u64 v[34:35], v[28:29], 0, v[140:141]
	global_store_dwordx4 v[34:35], v[108:111], off
	s_branch .LBB0_949
; DI unsigned pk2(float a, float b) { f32x2_t v = {a, b}; bf16x2_t r = __builtin_convertvector(v, bf16x2_t); return __builtin_bit_cast(unsigned, r); }
; DI void convert_w(const float* src, const float* src2, int srcN, int K, bf16_t* dst, int Nd, int mode) {
;     ...
;   for (size_t e = gid; e < total; e += gsz) {
;     int nd = (int)(e % Nd), k0 = (int)(e / Nd) * 8;
;     const float* s = src; int col = nd; bool valid = true;
;     if (mode == 0) { valid = nd < srcN; }
;     else if (mode == 1) { int g = nd >> 6, w = nd & 63; if (w < 32) col = g * 32 + w; else { s = src2; col = g * 32 + w - 32; } }
;     else { if (nd < 1024) col = (nd >> 7) * 192 + (nd & 127); else { int r = nd - 1024; col = (r >> 6) * 192 + 128 + (r & 63); } }
;     float v[8];
; #pragma unroll
;     for (int j = 0; j < 8; ++j) v[j] = valid ? s[(size_t)(k0 + j) * srcN + col] : 0.f;
;     uint4 o; o.x = pk2(v[0], v[1]); o.y = pk2(v[2], v[3]); o.z = pk2(v[4], v[5]); o.w = pk2(v[6], v[7]);
;     *(uint4*)(dst + (size_t)nd * K + k0) = o;
;   }
.Lcv2_n2:
	s_mov_b32 s31, s25
	s_lshr_b32 s24, s31, 4
	s_and_b32 s38, s31, 15
	s_mul_i32 s3, s38, 0x58000
	s_lshl_b32 s38, s38, 8
	s_lshl_b32 s37, s24, 4
	s_add_u32 s3, s3, s37
	s_lshl_b32 s37, s24, 15
	s_add_u32 s38, s38, s37
	s_mov_b32 s37, 0
	v_mov_b32_e32 v90, s3
	v_lshl_add_u64 v[30:31], v[10:11], 0, s[38:39]
	global_load_dword v40, v[30:31], off
	v_lshl_add_u64 v[32:33], v[12:13], 0, s[38:39]
	global_load_dword v41, v[32:33], off
	v_lshl_add_u64 v[30:31], v[14:15], 0, s[38:39]
	global_load_dword v42, v[30:31], off
	v_lshl_add_u64 v[32:33], v[16:17], 0, s[38:39]
	global_load_dword v43, v[32:33], off
	v_lshl_add_u64 v[30:31], v[18:19], 0, s[38:39]
	global_load_dword v44, v[30:31], off
	v_lshl_add_u64 v[32:33], v[20:21], 0, s[38:39]
	global_load_dword v45, v[32:33], off
	v_lshl_add_u64 v[30:31], v[22:23], 0, s[38:39]
	global_load_dword v46, v[30:31], off
	v_lshl_add_u64 v[32:33], v[24:25], 0, s[38:39]
	global_load_dword v47, v[32:33], off
	s_add_u32 s31, s31, s30
	s_lshr_b32 s24, s31, 4
	s_and_b32 s38, s31, 15
	s_mul_i32 s3, s38, 0x58000
	s_lshl_b32 s38, s38, 8
	s_lshl_b32 s37, s24, 4
	s_add_u32 s3, s3, s37
	s_lshl_b32 s37, s24, 15
	s_add_u32 s38, s38, s37
	s_mov_b32 s37, 0
	v_mov_b32_e32 v91, s3
	v_lshl_add_u64 v[30:31], v[10:11], 0, s[38:39]
	global_load_dword v48, v[30:31], off
	v_lshl_add_u64 v[32:33], v[12:13], 0, s[38:39]
	global_load_dword v49, v[32:33], off
	v_lshl_add_u64 v[30:31], v[14:15], 0, s[38:39]
	global_load_dword v50, v[30:31], off
	v_lshl_add_u64 v[32:33], v[16:17], 0, s[38:39]
	global_load_dword v51, v[32:33], off
	v_lshl_add_u64 v[30:31], v[18:19], 0, s[38:39]
	global_load_dword v52, v[30:31], off
	v_lshl_add_u64 v[32:33], v[20:21], 0, s[38:39]
	global_load_dword v53, v[32:33], off
	v_lshl_add_u64 v[30:31], v[22:23], 0, s[38:39]
	global_load_dword v54, v[30:31], off
	v_lshl_add_u64 v[32:33], v[24:25], 0, s[38:39]
	global_load_dword v55, v[32:33], off
	s_waitcnt vmcnt(8)
	v_cvt_pk_bf16_f32 v100, v40, v41
	v_cvt_pk_bf16_f32 v101, v42, v43
	v_cvt_pk_bf16_f32 v102, v44, v45
	v_cvt_pk_bf16_f32 v103, v46, v47
	v_mov_b32_e32 v140, v90
	v_lshl_add_u64 v[34:35], v[28:29], 0, v[140:141]
	global_store_dwordx4 v[34:35], v[100:103], off
	s_waitcnt vmcnt(1)
	v_cvt_pk_bf16_f32 v104, v48, v49
	v_cvt_pk_bf16_f32 v105, v50, v51
	v_cvt_pk_bf16_f32 v106, v52, v53
	v_cvt_pk_bf16_f32 v107, v54, v55
	v_mov_b32_e32 v140, v91
	v_lshl_add_u64 v[34:35], v[28:29], 0, v[140:141]
	global_store_dwordx4 v[34:35], v[104:107], off
	s_branch .LBB0_949
.Lcv2_old:
	s_mov_b64 s[30:31], 0
	s_movk_i32 s3, 0x1600
